# speedup vs baseline: 1.0069x; 1.0069x over previous
; __device__ __forceinline__ float partner_sum(float v) { auto rr = __builtin_amdgcn_permlane32_swap(__float_as_uint(v), __float_as_uint(v), false, false); return __uint_as_float(rr[0]) + __uint_as_float(rr[1]); }
; __device__ __forceinline__ void df_unit_p128(ATT_LAS unsigned char* lds, const bf16_t* Q, const bf16_t* __restrict__ K, const bf16_t* __restrict__ V, bf16_t* O, int b, int h, int qb,
;                                              float lam, float post, const float* __restrict__ sub_g, const int wv) {
;     ...
;     if (mp == 0) {
;         float ss = 0.f;
; #pragma unroll
;         for (int d0 = 0; d0 < 4; ++d0)
; #pragma unroll
;             for (int i = 0; i < 4; ++i) { const f32x4 x2 = xch[(d0 * 4 + i) * 64];
; #pragma unroll
;                 for (int jj = 0; jj < 4; ++jj) { const float v = o[d0][4 * i + jj] * inv - x2[jj]; o[d0][4 * i + jj] = v; ss += v * v; } }
;         ss = partner_sum(ss);
.LBB0_233:
	s_andn2_b64 vcc, exec, s[8:9]
	s_waitcnt vmcnt(0) lgkmcnt(0)
	s_barrier
	s_cbranch_vccnz .LBB0_235
	v_ashrrev_i32_e32 v208, 3, v4
	v_and_b32_e32 v208, -4, v208
	v_ashrrev_i32_e32 v209, 31, v208
	v_lshl_add_u64 v[206:207], v[208:209], 2, s[0:1]
	global_load_dwordx4 v[130:133], v[206:207], off
	global_load_dwordx4 v[134:137], v[206:207], off offset:32
	global_load_dwordx4 v[138:141], v[206:207], off offset:64
	global_load_dwordx4 v[142:145], v[206:207], off offset:96
	global_load_dwordx4 v[146:149], v[206:207], off offset:128
	global_load_dwordx4 v[150:153], v[206:207], off offset:160
	global_load_dwordx4 v[154:157], v[206:207], off offset:192
	global_load_dwordx4 v[158:161], v[206:207], off offset:224
	global_load_dwordx4 v[162:165], v[206:207], off offset:256
	global_load_dwordx4 v[166:169], v[206:207], off offset:288
	global_load_dwordx4 v[170:173], v[206:207], off offset:320
	global_load_dwordx4 v[174:177], v[206:207], off offset:352
	global_load_dwordx4 v[178:181], v[206:207], off offset:384
	global_load_dwordx4 v[182:185], v[206:207], off offset:416
	global_load_dwordx4 v[186:189], v[206:207], off offset:448
	global_load_dwordx4 v[190:193], v[206:207], off offset:480
	ds_read_b128 v[6:9], v2
	ds_read_b128 v[194:197], v2 offset:1024
	ds_read_b128 v[198:201], v2 offset:2048
	ds_read_b128 v[202:205], v2 offset:3072
	s_waitcnt lgkmcnt(3)
	v_fma_f32 v37, v66, v0, -v6
	v_fma_f32 v34, v67, v0, -v7
	v_fma_f32 v35, v68, v0, -v8
	v_fma_f32 v36, v69, v0, -v9
	v_mul_f32_e32 v3, v34, v34
	v_fmac_f32_e32 v3, v37, v37
	v_fmac_f32_e32 v3, v35, v35
	v_fmac_f32_e32 v3, v36, v36
	ds_read_b128 v[6:9], v2 offset:4096
	s_waitcnt lgkmcnt(3)
	v_fma_f32 v50, v70, v0, -v194
	v_fma_f32 v51, v71, v0, -v195
	v_fma_f32 v52, v72, v0, -v196
	v_fma_f32 v53, v73, v0, -v197
	v_fmac_f32_e32 v3, v50, v50
	v_fmac_f32_e32 v3, v51, v51
	v_fmac_f32_e32 v3, v52, v52
	v_fmac_f32_e32 v3, v53, v53
	ds_read_b128 v[194:197], v2 offset:5120
	s_waitcnt lgkmcnt(3)
	v_fma_f32 v58, v74, v0, -v198
	v_fma_f32 v54, v75, v0, -v199
	v_fma_f32 v46, v76, v0, -v200
	v_fma_f32 v42, v77, v0, -v201
	v_fmac_f32_e32 v3, v58, v58
	v_fmac_f32_e32 v3, v54, v54
	v_fmac_f32_e32 v3, v46, v46
	v_fmac_f32_e32 v3, v42, v42
	ds_read_b128 v[198:201], v2 offset:6144
	s_waitcnt lgkmcnt(3)
	v_fma_f32 v71, v78, v0, -v202
	v_fma_f32 v68, v79, v0, -v203
	v_fma_f32 v65, v80, v0, -v204
	v_fma_f32 v62, v81, v0, -v205
	v_fmac_f32_e32 v3, v71, v71
	v_fmac_f32_e32 v3, v68, v68
	v_fmac_f32_e32 v3, v65, v65
	v_fmac_f32_e32 v3, v62, v62
	ds_read_b128 v[202:205], v2 offset:7168
	s_waitcnt lgkmcnt(3)
	v_fma_f32 v59, v82, v0, -v6
	v_fma_f32 v55, v83, v0, -v7
	v_fma_f32 v47, v84, v0, -v8
	v_fma_f32 v43, v85, v0, -v9
	v_fmac_f32_e32 v3, v59, v59
	v_fmac_f32_e32 v3, v55, v55
	v_fmac_f32_e32 v3, v47, v47
	v_fmac_f32_e32 v3, v43, v43
	ds_read_b128 v[6:9], v2 offset:8192
	s_waitcnt lgkmcnt(3)
	v_fma_f32 v72, v86, v0, -v194
	v_fma_f32 v69, v87, v0, -v195
	v_fma_f32 v66, v88, v0, -v196
	v_fma_f32 v63, v89, v0, -v197
	v_fmac_f32_e32 v3, v72, v72
	v_fmac_f32_e32 v3, v69, v69
	v_fmac_f32_e32 v3, v66, v66
	v_fmac_f32_e32 v3, v63, v63
	ds_read_b128 v[194:197], v2 offset:9216
	s_waitcnt lgkmcnt(3)
	v_fma_f32 v60, v90, v0, -v198
	v_fma_f32 v56, v91, v0, -v199
	v_fma_f32 v48, v92, v0, -v200
	v_fma_f32 v44, v93, v0, -v201
	v_fmac_f32_e32 v3, v60, v60
	v_fmac_f32_e32 v3, v56, v56
	v_fmac_f32_e32 v3, v48, v48
	v_fmac_f32_e32 v3, v44, v44
	ds_read_b128 v[198:201], v2 offset:10240
	s_waitcnt lgkmcnt(3)
	v_fma_f32 v73, v94, v0, -v202
	v_fma_f32 v70, v95, v0, -v203
	v_fma_f32 v67, v96, v0, -v204
	v_fma_f32 v64, v97, v0, -v205
	v_fmac_f32_e32 v3, v73, v73
	v_fmac_f32_e32 v3, v70, v70
	v_fmac_f32_e32 v3, v67, v67
	v_fmac_f32_e32 v3, v64, v64
	ds_read_b128 v[202:205], v2 offset:11264
	s_waitcnt lgkmcnt(3)
	v_fma_f32 v61, v98, v0, -v6
	v_fma_f32 v57, v99, v0, -v7
	v_fma_f32 v49, v100, v0, -v8
	v_fma_f32 v45, v101, v0, -v9
	v_fmac_f32_e32 v3, v61, v61
	v_fmac_f32_e32 v3, v57, v57
	v_fmac_f32_e32 v3, v49, v49
	v_fmac_f32_e32 v3, v45, v45
	ds_read_b128 v[6:9], v2 offset:12288
	s_waitcnt lgkmcnt(3)
	v_fma_f32 v41, v102, v0, -v194
	v_fma_f32 v40, v103, v0, -v195
	v_fma_f32 v39, v104, v0, -v196
	v_fma_f32 v38, v105, v0, -v197
	v_fmac_f32_e32 v3, v41, v41
	v_fmac_f32_e32 v3, v40, v40
	v_fmac_f32_e32 v3, v39, v39
	v_fmac_f32_e32 v3, v38, v38
	ds_read_b128 v[194:197], v2 offset:13312
	s_waitcnt lgkmcnt(3)
	v_fma_f32 v33, v106, v0, -v198
	v_fma_f32 v32, v107, v0, -v199
	v_fma_f32 v31, v108, v0, -v200
	v_fma_f32 v30, v109, v0, -v201
	v_fmac_f32_e32 v3, v33, v33
	v_fmac_f32_e32 v3, v32, v32
	v_fmac_f32_e32 v3, v31, v31
	v_fmac_f32_e32 v3, v30, v30
	ds_read_b128 v[198:201], v2 offset:14336
	s_waitcnt lgkmcnt(3)
	v_fma_f32 v29, v110, v0, -v202
	v_fma_f32 v28, v111, v0, -v203
	v_fma_f32 v27, v112, v0, -v204
	v_fma_f32 v26, v113, v0, -v205
	v_fmac_f32_e32 v3, v29, v29
	v_fmac_f32_e32 v3, v28, v28
	v_fmac_f32_e32 v3, v27, v27
	v_fmac_f32_e32 v3, v26, v26
	ds_read_b128 v[202:205], v2 offset:15360
	s_waitcnt lgkmcnt(3)
	v_fma_f32 v25, v114, v0, -v6
	v_fma_f32 v24, v115, v0, -v7
	v_fma_f32 v23, v116, v0, -v8
	v_fma_f32 v22, v117, v0, -v9
	v_fmac_f32_e32 v3, v25, v25
	v_fmac_f32_e32 v3, v24, v24
	v_fmac_f32_e32 v3, v23, v23
	v_fmac_f32_e32 v3, v22, v22
	s_waitcnt lgkmcnt(2)
	v_fma_f32 v21, v118, v0, -v194
	v_fma_f32 v20, v119, v0, -v195
	v_fma_f32 v19, v120, v0, -v196
	v_fma_f32 v18, v121, v0, -v197
	v_fmac_f32_e32 v3, v21, v21
	v_fmac_f32_e32 v3, v20, v20
	v_fmac_f32_e32 v3, v19, v19
	v_fmac_f32_e32 v3, v18, v18
	s_waitcnt lgkmcnt(1)
; __device__ __forceinline__ unsigned cvtpk(float lo, float hi) { unsigned r; asm volatile("v_cvt_pk_bf16_f32 %0, %1, %2" : "=v"(r) : "v"(lo), "v"(hi)); return r; }
; __device__ __forceinline__ float partner_sum(float v) { auto rr = __builtin_amdgcn_permlane32_swap(__float_as_uint(v), __float_as_uint(v), false, false); return __uint_as_float(rr[0]) + __uint_as_float(rr[1]); }
; __device__ __forceinline__ void df_unit_p128(ATT_LAS unsigned char* lds, const bf16_t* Q, const bf16_t* __restrict__ K, const bf16_t* __restrict__ V, bf16_t* O, int b, int h, int qb,
;                                              float lam, float post, const float* __restrict__ sub_g, const int wv) {
;     ...
;             for (int i = 0; i < 4; ++i) { const f32x4 x2 = xch[(d0 * 4 + i) * 64];
; #pragma unroll
;                 for (int jj = 0; jj < 4; ++jj) { const float v = o[d0][4 * i + jj] * inv - x2[jj]; o[d0][4 * i + jj] = v; ss += v * v; } }
;         ss = partner_sum(ss);
;         const float rs = __builtin_amdgcn_rsqf(ss * (1.0f / 128.0f) + 1e-6f) * post;
;         bf16_t* Ow = O + (rowbase + q0 + rg * 32 + r32e) * DM + h * 128 + 4 * hie;
; #pragma unroll
;         for (int d0 = 0; d0 < 4; ++d0)
; #pragma unroll
;             for (int i = 0; i < 4; ++i) { const f32x4 g = *(const f32x4*)(sub_g + d0 * 32 + 8 * i + 4 * hie);
;                 u32x2 w; w.x = cvtpk(o[d0][4 * i] * rs * g[0], o[d0][4 * i + 1] * rs * g[1]); w.y = cvtpk(o[d0][4 * i + 2] * rs * g[2], o[d0][4 * i + 3] * rs * g[3]);
;                 *(u32x2*)(Ow + d0 * 32 + 8 * i) = w; }
	v_fma_f32 v17, v122, v0, -v198
	v_fma_f32 v16, v123, v0, -v199
	v_fma_f32 v15, v124, v0, -v200
	v_fma_f32 v14, v125, v0, -v201
	v_fmac_f32_e32 v3, v17, v17
	v_fmac_f32_e32 v3, v16, v16
	v_fmac_f32_e32 v3, v15, v15
	v_fmac_f32_e32 v3, v14, v14
	s_waitcnt lgkmcnt(0)
	v_fma_f32 v13, v126, v0, -v202
	v_fmac_f32_e32 v3, v13, v13
	v_fma_f32 v12, v127, v0, -v203
	v_fmac_f32_e32 v3, v12, v12
	v_fma_f32 v10, v128, v0, -v204
	v_fmac_f32_e32 v3, v10, v10
	v_fma_f32 v0, v129, v0, -v205
	v_fmac_f32_e32 v3, v0, v0
	v_mov_b32_e32 v2, v3
	s_nop 1
	v_permlane32_swap_b32_e32 v3, v2
	v_add_f32_e32 v2, v3, v2
	v_fmamk_f32 v2, v2, 0x3c000000, v240
	v_rsq_f32_e32 v2, v2
	v_mov_b32_e32 v3, s27
	v_mul_f32_e32 v11, v245, v2
	v_and_or_b32 v2, v4, 31, s26
	v_ashrrev_i32_e32 v4, 3, v4
	v_lshlrev_b64 v[2:3], 11, v[2:3]
	v_and_b32_e32 v4, -4, v4
	v_lshl_add_u64 v[2:3], s[56:57], 0, v[2:3]
	v_ashrrev_i32_e32 v5, 31, v4
	v_lshl_add_u64 v[2:3], v[2:3], 0, s[54:55]
	v_lshl_add_u64 v[8:9], v[4:5], 2, s[0:1]
	v_lshl_add_u64 v[6:7], v[4:5], 1, v[2:3]
	v_mul_f32_e32 v37, v37, v11
	v_mul_f32_e32 v34, v34, v11
	v_mul_f32_e32 v33, v33, v11
	v_mul_f32_e32 v32, v32, v11
	v_mul_f32_e32 v29, v29, v11
	v_mul_f32_e32 v28, v28, v11
	v_mul_f32_e32 v25, v25, v11
	v_mul_f32_e32 v24, v24, v11
	v_mul_f32_e32 v21, v21, v11
	v_mul_f32_e32 v20, v20, v11
	v_mul_f32_e32 v17, v17, v11
	v_mul_f32_e32 v16, v16, v11
	v_mul_f32_e32 v0, v0, v11
	s_waitcnt vmcnt(0)
	v_mul_f32_e32 v2, v130, v37
	v_mul_f32_e32 v3, v131, v34
	v_cvt_pk_bf16_f32 v2, v2, v3
	v_mul_f32_e32 v3, v35, v11
	v_mul_f32_e32 v3, v132, v3
	v_mul_f32_e32 v4, v36, v11
	v_mul_f32_e32 v4, v133, v4
	v_cvt_pk_bf16_f32 v3, v3, v4
	global_store_dwordx2 v[6:7], v[2:3], off
	v_mul_f32_e32 v34, v50, v11
	v_mul_f32_e32 v2, v134, v34
	v_mul_f32_e32 v34, v51, v11
	v_mul_f32_e32 v3, v135, v34
	v_cvt_pk_bf16_f32 v2, v2, v3
	v_mul_f32_e32 v3, v52, v11
	v_mul_f32_e32 v3, v136, v3
	v_mul_f32_e32 v4, v53, v11
	v_mul_f32_e32 v4, v137, v4
	v_cvt_pk_bf16_f32 v3, v3, v4
	global_store_dwordx2 v[6:7], v[2:3], off offset:16
	v_mul_f32_e32 v34, v58, v11
	v_mul_f32_e32 v2, v34, v138
	v_mul_f32_e32 v34, v54, v11
	v_mul_f32_e32 v3, v34, v139
	v_cvt_pk_bf16_f32 v2, v2, v3
	v_mul_f32_e32 v3, v46, v11
	v_mul_f32_e32 v3, v3, v140
	v_mul_f32_e32 v4, v42, v11
	v_mul_f32_e32 v4, v4, v141
	v_cvt_pk_bf16_f32 v3, v3, v4
	global_store_dwordx2 v[6:7], v[2:3], off offset:32
	v_mul_f32_e32 v34, v71, v11
	v_mul_f32_e32 v2, v34, v142
	v_mul_f32_e32 v34, v68, v11
	v_mul_f32_e32 v3, v34, v143
	v_cvt_pk_bf16_f32 v2, v2, v3
	v_mul_f32_e32 v3, v65, v11
	v_mul_f32_e32 v3, v3, v144
	v_mul_f32_e32 v4, v62, v11
	v_mul_f32_e32 v4, v4, v145
	v_cvt_pk_bf16_f32 v3, v3, v4
	global_store_dwordx2 v[6:7], v[2:3], off offset:48
	v_mul_f32_e32 v34, v59, v11
	v_mul_f32_e32 v2, v34, v146
	v_mul_f32_e32 v34, v55, v11
	v_mul_f32_e32 v3, v34, v147
	v_cvt_pk_bf16_f32 v2, v2, v3
	v_mul_f32_e32 v3, v47, v11
	v_mul_f32_e32 v3, v3, v148
	v_mul_f32_e32 v4, v43, v11
	v_mul_f32_e32 v4, v4, v149
	v_cvt_pk_bf16_f32 v3, v3, v4
	global_store_dwordx2 v[6:7], v[2:3], off offset:64
	v_mul_f32_e32 v34, v72, v11
	v_mul_f32_e32 v2, v34, v150
	v_mul_f32_e32 v34, v69, v11
	v_mul_f32_e32 v3, v34, v151
	v_cvt_pk_bf16_f32 v2, v2, v3
	v_mul_f32_e32 v3, v66, v11
	v_mul_f32_e32 v3, v3, v152
	v_mul_f32_e32 v4, v63, v11
	v_mul_f32_e32 v4, v4, v153
	v_cvt_pk_bf16_f32 v3, v3, v4
	global_store_dwordx2 v[6:7], v[2:3], off offset:80
	v_mul_f32_e32 v34, v60, v11
	v_mul_f32_e32 v2, v34, v154
	v_mul_f32_e32 v34, v56, v11
	v_mul_f32_e32 v3, v34, v155
	v_cvt_pk_bf16_f32 v2, v2, v3
	v_mul_f32_e32 v3, v48, v11
	v_mul_f32_e32 v3, v3, v156
	v_mul_f32_e32 v4, v44, v11
	v_mul_f32_e32 v4, v4, v157
	v_cvt_pk_bf16_f32 v3, v3, v4
	global_store_dwordx2 v[6:7], v[2:3], off offset:96
	v_mul_f32_e32 v34, v73, v11
	v_mul_f32_e32 v2, v34, v158
	v_mul_f32_e32 v34, v70, v11
	v_mul_f32_e32 v3, v34, v159
	v_cvt_pk_bf16_f32 v2, v2, v3
	v_mul_f32_e32 v3, v67, v11
	v_mul_f32_e32 v3, v3, v160
	v_mul_f32_e32 v4, v64, v11
	v_mul_f32_e32 v4, v4, v161
	v_cvt_pk_bf16_f32 v3, v3, v4
	global_store_dwordx2 v[6:7], v[2:3], off offset:112
	v_mul_f32_e32 v34, v61, v11
	v_mul_f32_e32 v2, v34, v162
	v_mul_f32_e32 v34, v57, v11
	v_mul_f32_e32 v3, v34, v163
	v_cvt_pk_bf16_f32 v2, v2, v3
	v_mul_f32_e32 v3, v49, v11
	v_mul_f32_e32 v3, v3, v164
	v_mul_f32_e32 v4, v45, v11
	v_mul_f32_e32 v4, v4, v165
	v_cvt_pk_bf16_f32 v3, v3, v4
	global_store_dwordx2 v[6:7], v[2:3], off offset:128
	v_mul_f32_e32 v34, v41, v11
	v_mul_f32_e32 v2, v34, v166
	v_mul_f32_e32 v34, v40, v11
	v_mul_f32_e32 v3, v34, v167
	v_cvt_pk_bf16_f32 v2, v2, v3
	v_mul_f32_e32 v3, v39, v11
	v_mul_f32_e32 v3, v3, v168
	v_mul_f32_e32 v4, v38, v11
	v_mul_f32_e32 v4, v4, v169
	v_cvt_pk_bf16_f32 v3, v3, v4
	global_store_dwordx2 v[6:7], v[2:3], off offset:144
	v_mul_f32_e32 v2, v33, v170
	v_mul_f32_e32 v3, v32, v171
	v_cvt_pk_bf16_f32 v2, v2, v3
	v_mul_f32_e32 v3, v31, v11
	v_mul_f32_e32 v3, v3, v172
	v_mul_f32_e32 v4, v30, v11
	v_mul_f32_e32 v4, v4, v173
	v_cvt_pk_bf16_f32 v3, v3, v4
	global_store_dwordx2 v[6:7], v[2:3], off offset:160
	v_mul_f32_e32 v2, v29, v174
	v_mul_f32_e32 v3, v28, v175
	v_cvt_pk_bf16_f32 v2, v2, v3
	v_mul_f32_e32 v3, v27, v11
	v_mul_f32_e32 v3, v3, v176
	v_mul_f32_e32 v4, v26, v11
	v_mul_f32_e32 v4, v4, v177
	v_cvt_pk_bf16_f32 v3, v3, v4
	global_store_dwordx2 v[6:7], v[2:3], off offset:176
	v_mul_f32_e32 v2, v25, v178
	v_mul_f32_e32 v3, v24, v179
	v_cvt_pk_bf16_f32 v2, v2, v3
	v_mul_f32_e32 v3, v23, v11
	v_mul_f32_e32 v3, v3, v180
	v_mul_f32_e32 v4, v22, v11
	v_mul_f32_e32 v4, v4, v181
	v_cvt_pk_bf16_f32 v3, v3, v4
	global_store_dwordx2 v[6:7], v[2:3], off offset:192
	v_mul_f32_e32 v2, v21, v182
	v_mul_f32_e32 v3, v20, v183
	v_cvt_pk_bf16_f32 v2, v2, v3
	v_mul_f32_e32 v3, v19, v11
	v_mul_f32_e32 v3, v3, v184
	v_mul_f32_e32 v4, v18, v11
	v_mul_f32_e32 v4, v4, v185
	v_cvt_pk_bf16_f32 v3, v3, v4
	global_store_dwordx2 v[6:7], v[2:3], off offset:208
	v_mul_f32_e32 v2, v17, v186
	v_mul_f32_e32 v3, v16, v187
	v_cvt_pk_bf16_f32 v2, v2, v3
	v_mul_f32_e32 v3, v15, v11
	v_mul_f32_e32 v3, v3, v188
	v_mul_f32_e32 v4, v14, v11
	v_mul_f32_e32 v4, v4, v189
	v_cvt_pk_bf16_f32 v3, v3, v4
	global_store_dwordx2 v[6:7], v[2:3], off offset:224
	v_mul_f32_e32 v8, v13, v11
	v_mul_f32_e32 v2, v8, v190
	v_mul_f32_e32 v8, v12, v11
	v_mul_f32_e32 v3, v8, v191
	v_cvt_pk_bf16_f32 v2, v2, v3
	v_mul_f32_e32 v3, v10, v11
	v_mul_f32_e32 v3, v3, v192
	v_mul_f32_e32 v0, v0, v193
	v_cvt_pk_bf16_f32 v3, v3, v0
	global_store_dwordx2 v[6:7], v[2:3], off offset:240
